# sbcanon + down-projection K-loop heads (both layers) moved from 0/4 to 56 mod 64 bytes, later code offsets kept
# baseline (speedup 1.0000x reference)
.LBB0_851:
	s_ashr_i32 s17, s16, 31
	s_lshl_b64 s[18:19], s[16:17], 21
	s_add_u32 s18, s80, s18
	s_addc_u32 s19, s81, s19
	s_and_b64 s[20:21], s[4:5], exec
	s_cselect_b32 s3, s19, s27
	s_cselect_b32 s17, s18, s26
	s_ashr_i32 s15, s14, 31
	s_lshl_b64 s[20:21], s[14:15], 21
	s_add_u32 s20, s39, s20
	s_addc_u32 s21, s40, s21
	s_and_b64 s[30:31], s[4:5], exec
	s_cselect_b32 s15, s21, s29
	s_cselect_b32 s23, s20, s28
	s_add_u32 s90, s28, 0x100
	s_addc_u32 s91, s29, 0
	s_mov_b32 s92, -2
	s_waitcnt lgkmcnt(0)
	s_nop 0
	ds_read_b128 v[128:131], v211
	ds_read_b128 v[132:135], v211 offset:1024
	ds_read_b128 v[136:139], v211 offset:2048
	ds_read_b128 v[140:143], v211 offset:3072
	ds_read_b128 v[144:147], v212
	ds_read_b128 v[148:151], v212 offset:1024
	ds_read_b128 v[152:155], v212 offset:2048
	ds_read_b128 v[156:159], v212 offset:3072
	s_add_u32 s28, s26, 0x100
	s_addc_u32 s29, s27, 0
	s_cmp_eq_u32 s92, 60
	s_cselect_b32 s35, s3, s29
	s_cselect_b32 s34, s17, s28
	s_cselect_b32 s31, s15, s91
	s_cselect_b32 s30, s23, s90
	v_lshl_add_u64 v[204:205], s[26:27], 0, v[180:181]
	s_add_i32 m0, s25, 0xc000
	ds_read_b128 v[160:163], v213
	ds_read_b128 v[164:167], v213 offset:1024
	ds_read_b128 v[168:171], v213 offset:2048
	ds_read_b128 v[172:175], v213 offset:3072
	ds_read_b128 v[188:191], v213 offset:4096
	ds_read_b128 v[192:195], v213 offset:5120
	ds_read_b128 v[196:199], v213 offset:6144
	ds_read_b128 v[200:203], v213 offset:7168
	global_load_lds_dwordx4 v[204:205], off
	v_lshl_add_u64 v[204:205], s[26:27], 0, v[182:183]
	s_add_i32 m0, s25, 0xe000
	s_nop 0
	global_load_lds_dwordx4 v[204:205], off
	s_waitcnt vmcnt(8)
	s_waitcnt lgkmcnt(0)
	s_setprio 1
	s_barrier
	v_mfma_f32_16x16x32_bf16 v[124:127], v[128:131], v[160:163], 0
	v_mfma_f32_16x16x32_bf16 v[120:123], v[136:139], v[160:163], 0
	v_mfma_f32_16x16x32_bf16 v[108:111], v[128:131], v[168:171], 0
	v_mfma_f32_16x16x32_bf16 v[104:107], v[136:139], v[168:171], 0
	v_mfma_f32_16x16x32_bf16 v[92:95], v[128:131], v[188:191], 0
	v_mfma_f32_16x16x32_bf16 v[88:91], v[136:139], v[188:191], 0
	v_mfma_f32_16x16x32_bf16 v[76:79], v[128:131], v[196:199], 0
	v_mfma_f32_16x16x32_bf16 v[72:75], v[136:139], v[196:199], 0
	v_mfma_f32_16x16x32_bf16 v[124:127], v[132:135], v[164:167], v[124:127]
	v_mfma_f32_16x16x32_bf16 v[120:123], v[140:143], v[164:167], v[120:123]
	v_mfma_f32_16x16x32_bf16 v[108:111], v[132:135], v[172:175], v[108:111]
	v_mfma_f32_16x16x32_bf16 v[104:107], v[140:143], v[172:175], v[104:107]
	v_mfma_f32_16x16x32_bf16 v[92:95], v[132:135], v[192:195], v[92:95]
	v_mfma_f32_16x16x32_bf16 v[88:91], v[140:143], v[192:195], v[88:91]
	v_mfma_f32_16x16x32_bf16 v[76:79], v[132:135], v[200:203], v[76:79]
	v_mfma_f32_16x16x32_bf16 v[72:75], v[140:143], v[200:203], v[72:75]
	s_setprio 0
	s_setprio 1
	v_mfma_f32_16x16x32_bf16 v[116:119], v[144:147], v[160:163], 0
	v_mfma_f32_16x16x32_bf16 v[112:115], v[152:155], v[160:163], 0
	v_mfma_f32_16x16x32_bf16 v[100:103], v[144:147], v[168:171], 0
	v_mfma_f32_16x16x32_bf16 v[96:99], v[152:155], v[168:171], 0
	v_mfma_f32_16x16x32_bf16 v[84:87], v[144:147], v[188:191], 0
	v_mfma_f32_16x16x32_bf16 v[80:83], v[152:155], v[188:191], 0
	v_mfma_f32_16x16x32_bf16 v[68:71], v[144:147], v[196:199], 0
	v_mfma_f32_16x16x32_bf16 v[64:67], v[152:155], v[196:199], 0
	v_mfma_f32_16x16x32_bf16 v[116:119], v[148:151], v[164:167], v[116:119]
	v_mfma_f32_16x16x32_bf16 v[112:115], v[156:159], v[164:167], v[112:115]
	v_mfma_f32_16x16x32_bf16 v[100:103], v[148:151], v[172:175], v[100:103]
	v_mfma_f32_16x16x32_bf16 v[96:99], v[156:159], v[172:175], v[96:99]
	v_mfma_f32_16x16x32_bf16 v[84:87], v[148:151], v[192:195], v[84:87]
	v_mfma_f32_16x16x32_bf16 v[80:83], v[156:159], v[192:195], v[80:83]
	v_mfma_f32_16x16x32_bf16 v[68:71], v[148:151], v[200:203], v[68:71]
	v_mfma_f32_16x16x32_bf16 v[64:67], v[156:159], v[200:203], v[64:67]
	s_barrier
	s_setprio 0
	s_add_i32 s26, s88, s41
	v_lshl_add_u64 v[204:205], s[30:31], 0, v[176:177]
	s_mov_b32 m0, s26
	ds_read_b128 v[160:163], v213 offset:16384
	ds_read_b128 v[164:167], v213 offset:17408
	ds_read_b128 v[168:171], v213 offset:18432
	ds_read_b128 v[172:175], v213 offset:19456
	ds_read_b128 v[188:191], v213 offset:20480
	ds_read_b128 v[192:195], v213 offset:21504
	ds_read_b128 v[196:199], v213 offset:22528
	ds_read_b128 v[200:203], v213 offset:23552
	global_load_lds_dwordx4 v[204:205], off
	s_add_i32 m0, s26, 0x2000
	s_add_u32 s26, s30, 0x100000
	v_lshl_add_u64 v[216:217], s[30:31], 0, v[178:179]
	s_addc_u32 s27, s31, 0
	s_add_i32 s93, s89, s41
	global_load_lds_dwordx4 v[216:217], off
	v_lshl_add_u64 v[218:219], s[26:27], 0, v[176:177]
	s_mov_b32 m0, s93
	v_lshl_add_u64 v[220:221], s[34:35], 0, v[178:179]
	global_load_lds_dwordx4 v[218:219], off
	v_lshl_add_u64 v[218:219], s[26:27], 0, v[178:179]
	s_add_i32 m0, s93, 0x2000
	s_nop 0
	global_load_lds_dwordx4 v[218:219], off
	v_lshl_add_u64 v[218:219], s[34:35], 0, v[176:177]
	s_mov_b32 m0, s25
	s_nop 0
	global_load_lds_dwordx4 v[218:219], off
	s_mov_b32 m0, s50
	s_nop 0
	global_load_lds_dwordx4 v[220:221], off
	s_waitcnt vmcnt(8)
	s_waitcnt lgkmcnt(0)
	s_setprio 1
	s_barrier
	v_mfma_f32_16x16x32_bf16 v[60:63], v[128:131], v[160:163], 0
	v_mfma_f32_16x16x32_bf16 v[56:59], v[136:139], v[160:163], 0
	v_mfma_f32_16x16x32_bf16 v[44:47], v[128:131], v[168:171], 0
	v_mfma_f32_16x16x32_bf16 v[40:43], v[136:139], v[168:171], 0
	v_mfma_f32_16x16x32_bf16 v[28:31], v[128:131], v[188:191], 0
	v_mfma_f32_16x16x32_bf16 v[24:27], v[136:139], v[188:191], 0
	v_mfma_f32_16x16x32_bf16 v[12:15], v[128:131], v[196:199], 0
	v_mfma_f32_16x16x32_bf16 v[8:11], v[136:139], v[196:199], 0
	v_mfma_f32_16x16x32_bf16 v[60:63], v[132:135], v[164:167], v[60:63]
	v_mfma_f32_16x16x32_bf16 v[56:59], v[140:143], v[164:167], v[56:59]
	v_mfma_f32_16x16x32_bf16 v[44:47], v[132:135], v[172:175], v[44:47]
	v_mfma_f32_16x16x32_bf16 v[40:43], v[140:143], v[172:175], v[40:43]
	v_mfma_f32_16x16x32_bf16 v[28:31], v[132:135], v[192:195], v[28:31]
	v_mfma_f32_16x16x32_bf16 v[24:27], v[140:143], v[192:195], v[24:27]
	v_mfma_f32_16x16x32_bf16 v[12:15], v[132:135], v[200:203], v[12:15]
	v_mfma_f32_16x16x32_bf16 v[8:11], v[140:143], v[200:203], v[8:11]
	s_setprio 0
	s_setprio 1
	v_mfma_f32_16x16x32_bf16 v[52:55], v[144:147], v[160:163], 0
	v_mfma_f32_16x16x32_bf16 v[48:51], v[152:155], v[160:163], 0
	v_mfma_f32_16x16x32_bf16 v[36:39], v[144:147], v[168:171], 0
	v_mfma_f32_16x16x32_bf16 v[32:35], v[152:155], v[168:171], 0
	v_mfma_f32_16x16x32_bf16 v[20:23], v[144:147], v[188:191], 0
	v_mfma_f32_16x16x32_bf16 v[16:19], v[152:155], v[188:191], 0
	v_mfma_f32_16x16x32_bf16 v[4:7], v[144:147], v[196:199], 0
	v_mfma_f32_16x16x32_bf16 v[0:3], v[152:155], v[196:199], 0
	v_mfma_f32_16x16x32_bf16 v[52:55], v[148:151], v[164:167], v[52:55]
	v_mfma_f32_16x16x32_bf16 v[48:51], v[156:159], v[164:167], v[48:51]
	v_mfma_f32_16x16x32_bf16 v[36:39], v[148:151], v[172:175], v[36:39]
	v_mfma_f32_16x16x32_bf16 v[32:35], v[156:159], v[172:175], v[32:35]
	v_mfma_f32_16x16x32_bf16 v[20:23], v[148:151], v[192:195], v[20:23]
	v_mfma_f32_16x16x32_bf16 v[16:19], v[156:159], v[192:195], v[16:19]
	v_mfma_f32_16x16x32_bf16 v[4:7], v[148:151], v[200:203], v[4:7]
	v_mfma_f32_16x16x32_bf16 v[0:3], v[156:159], v[200:203], v[0:3]
	s_barrier
	s_setprio 0
	s_add_i32 s93, 0, 0x18000
	s_add_i32 s94, 0, 0x1c000
	v_add_u32_e32 v140, s93, v209
	v_add_u32_e32 v156, s94, v209
	ds_read_b128 v[128:131], v140
	ds_read_b128 v[132:135], v140 offset:1024
	ds_read_b128 v[136:139], v140 offset:2048
	ds_read_b128 v[140:143], v140 offset:3072
	ds_read_b128 v[144:147], v156
	ds_read_b128 v[148:151], v156 offset:1024
	ds_read_b128 v[152:155], v156 offset:2048
	ds_read_b128 v[156:159], v156 offset:3072
	s_add_u32 s26, s34, 0x100000
	s_addc_u32 s27, s35, 0
	s_mov_b32 m0, s51
	v_lshl_add_u64 v[222:223], s[26:27], 0, v[176:177]
	ds_read_b128 v[160:163], v213 offset:32768
	ds_read_b128 v[164:167], v213 offset:33792
	ds_read_b128 v[168:171], v213 offset:34816
	ds_read_b128 v[172:175], v213 offset:35840
	ds_read_b128 v[188:191], v213 offset:36864
	ds_read_b128 v[192:195], v213 offset:37888
	ds_read_b128 v[196:199], v213 offset:38912
	ds_read_b128 v[200:203], v213 offset:39936
	global_load_lds_dwordx4 v[222:223], off
	v_lshl_add_u64 v[222:223], s[26:27], 0, v[178:179]
	s_mov_b32 m0, s76
	s_nop 0
	global_load_lds_dwordx4 v[222:223], off
	s_waitcnt vmcnt(8)
	s_waitcnt lgkmcnt(0)
	s_setprio 1
	s_barrier
	v_mfma_f32_16x16x32_bf16 v[124:127], v[128:131], v[160:163], v[124:127]
	v_mfma_f32_16x16x32_bf16 v[120:123], v[136:139], v[160:163], v[120:123]
	v_mfma_f32_16x16x32_bf16 v[108:111], v[128:131], v[168:171], v[108:111]
	v_mfma_f32_16x16x32_bf16 v[104:107], v[136:139], v[168:171], v[104:107]
	v_mfma_f32_16x16x32_bf16 v[92:95], v[128:131], v[188:191], v[92:95]
	v_mfma_f32_16x16x32_bf16 v[88:91], v[136:139], v[188:191], v[88:91]
	v_mfma_f32_16x16x32_bf16 v[76:79], v[128:131], v[196:199], v[76:79]
	v_mfma_f32_16x16x32_bf16 v[72:75], v[136:139], v[196:199], v[72:75]
	v_mfma_f32_16x16x32_bf16 v[124:127], v[132:135], v[164:167], v[124:127]
	v_mfma_f32_16x16x32_bf16 v[120:123], v[140:143], v[164:167], v[120:123]
	v_mfma_f32_16x16x32_bf16 v[108:111], v[132:135], v[172:175], v[108:111]
	v_mfma_f32_16x16x32_bf16 v[104:107], v[140:143], v[172:175], v[104:107]
	v_mfma_f32_16x16x32_bf16 v[92:95], v[132:135], v[192:195], v[92:95]
	v_mfma_f32_16x16x32_bf16 v[88:91], v[140:143], v[192:195], v[88:91]
	v_mfma_f32_16x16x32_bf16 v[76:79], v[132:135], v[200:203], v[76:79]
	v_mfma_f32_16x16x32_bf16 v[72:75], v[140:143], v[200:203], v[72:75]
	s_setprio 0
	s_setprio 1
	v_mfma_f32_16x16x32_bf16 v[116:119], v[144:147], v[160:163], v[116:119]
	v_mfma_f32_16x16x32_bf16 v[112:115], v[152:155], v[160:163], v[112:115]
	v_mfma_f32_16x16x32_bf16 v[100:103], v[144:147], v[168:171], v[100:103]
	v_mfma_f32_16x16x32_bf16 v[96:99], v[152:155], v[168:171], v[96:99]
	v_mfma_f32_16x16x32_bf16 v[84:87], v[144:147], v[188:191], v[84:87]
	v_mfma_f32_16x16x32_bf16 v[80:83], v[152:155], v[188:191], v[80:83]
	v_mfma_f32_16x16x32_bf16 v[68:71], v[144:147], v[196:199], v[68:71]
	v_mfma_f32_16x16x32_bf16 v[64:67], v[152:155], v[196:199], v[64:67]
	v_mfma_f32_16x16x32_bf16 v[116:119], v[148:151], v[164:167], v[116:119]
	v_mfma_f32_16x16x32_bf16 v[112:115], v[156:159], v[164:167], v[112:115]
	v_mfma_f32_16x16x32_bf16 v[100:103], v[148:151], v[172:175], v[100:103]
	v_mfma_f32_16x16x32_bf16 v[96:99], v[156:159], v[172:175], v[96:99]
	v_mfma_f32_16x16x32_bf16 v[84:87], v[148:151], v[192:195], v[84:87]
	v_mfma_f32_16x16x32_bf16 v[80:83], v[156:159], v[192:195], v[80:83]
	v_mfma_f32_16x16x32_bf16 v[68:71], v[148:151], v[200:203], v[68:71]
	v_mfma_f32_16x16x32_bf16 v[64:67], v[156:159], v[200:203], v[64:67]
	s_barrier
	s_setprio 0
	s_add_i32 s26, s93, s41
	v_lshl_add_u64 v[204:205], v[204:205], 0, s[10:11]
	s_mov_b32 m0, s26
	ds_read_b128 v[160:163], v213 offset:49152
	ds_read_b128 v[164:167], v213 offset:50176
	ds_read_b128 v[168:171], v213 offset:51200
	ds_read_b128 v[172:175], v213 offset:52224
	ds_read_b128 v[188:191], v213 offset:53248
	ds_read_b128 v[192:195], v213 offset:54272
	ds_read_b128 v[196:199], v213 offset:55296
	ds_read_b128 v[200:203], v213 offset:56320
	global_load_lds_dwordx4 v[204:205], off
	s_add_i32 m0, s26, 0x2000
	s_add_u32 s26, s30, 0x100080
	v_lshl_add_u64 v[204:205], v[216:217], 0, s[10:11]
	s_addc_u32 s27, s31, 0
	s_add_i32 s30, s94, s41
	global_load_lds_dwordx4 v[204:205], off
	v_lshl_add_u64 v[204:205], s[26:27], 0, v[176:177]
	s_mov_b32 m0, s30
	s_nop 0
	global_load_lds_dwordx4 v[204:205], off
	v_lshl_add_u64 v[204:205], s[26:27], 0, v[178:179]
	s_add_i32 m0, s30, 0x2000
	s_nop 0
	global_load_lds_dwordx4 v[204:205], off
	v_lshl_add_u64 v[204:205], v[218:219], 0, s[10:11]
	s_mov_b32 m0, s78
	s_nop 0
	global_load_lds_dwordx4 v[204:205], off
	v_lshl_add_u64 v[204:205], v[220:221], 0, s[10:11]
	s_mov_b32 m0, s79
	s_nop 0
	global_load_lds_dwordx4 v[204:205], off
	s_waitcnt vmcnt(8)
	s_waitcnt lgkmcnt(0)
	s_setprio 1
	s_barrier
	v_mfma_f32_16x16x32_bf16 v[60:63], v[128:131], v[160:163], v[60:63]
	v_mfma_f32_16x16x32_bf16 v[56:59], v[136:139], v[160:163], v[56:59]
	v_mfma_f32_16x16x32_bf16 v[44:47], v[128:131], v[168:171], v[44:47]
	v_mfma_f32_16x16x32_bf16 v[40:43], v[136:139], v[168:171], v[40:43]
	v_mfma_f32_16x16x32_bf16 v[28:31], v[128:131], v[188:191], v[28:31]
	v_mfma_f32_16x16x32_bf16 v[24:27], v[136:139], v[188:191], v[24:27]
	v_mfma_f32_16x16x32_bf16 v[12:15], v[128:131], v[196:199], v[12:15]
	v_mfma_f32_16x16x32_bf16 v[8:11], v[136:139], v[196:199], v[8:11]
	v_mfma_f32_16x16x32_bf16 v[60:63], v[132:135], v[164:167], v[60:63]
	v_mfma_f32_16x16x32_bf16 v[56:59], v[140:143], v[164:167], v[56:59]
	v_mfma_f32_16x16x32_bf16 v[44:47], v[132:135], v[172:175], v[44:47]
	v_mfma_f32_16x16x32_bf16 v[40:43], v[140:143], v[172:175], v[40:43]
	v_mfma_f32_16x16x32_bf16 v[28:31], v[132:135], v[192:195], v[28:31]
	v_mfma_f32_16x16x32_bf16 v[24:27], v[140:143], v[192:195], v[24:27]
	v_mfma_f32_16x16x32_bf16 v[12:15], v[132:135], v[200:203], v[12:15]
	v_mfma_f32_16x16x32_bf16 v[8:11], v[140:143], v[200:203], v[8:11]
	s_setprio 0
	s_setprio 1
	v_mfma_f32_16x16x32_bf16 v[52:55], v[144:147], v[160:163], v[52:55]
	v_mfma_f32_16x16x32_bf16 v[48:51], v[152:155], v[160:163], v[48:51]
	v_mfma_f32_16x16x32_bf16 v[36:39], v[144:147], v[168:171], v[36:39]
	v_mfma_f32_16x16x32_bf16 v[32:35], v[152:155], v[168:171], v[32:35]
	v_mfma_f32_16x16x32_bf16 v[20:23], v[144:147], v[188:191], v[20:23]
	v_mfma_f32_16x16x32_bf16 v[16:19], v[152:155], v[188:191], v[16:19]
	v_mfma_f32_16x16x32_bf16 v[4:7], v[144:147], v[196:199], v[4:7]
	v_mfma_f32_16x16x32_bf16 v[0:3], v[152:155], v[196:199], v[0:3]
	v_mfma_f32_16x16x32_bf16 v[52:55], v[148:151], v[164:167], v[52:55]
	v_mfma_f32_16x16x32_bf16 v[48:51], v[156:159], v[164:167], v[48:51]
	v_mfma_f32_16x16x32_bf16 v[36:39], v[148:151], v[172:175], v[36:39]
	v_mfma_f32_16x16x32_bf16 v[32:35], v[156:159], v[172:175], v[32:35]
	v_mfma_f32_16x16x32_bf16 v[20:23], v[148:151], v[192:195], v[20:23]
	v_mfma_f32_16x16x32_bf16 v[16:19], v[156:159], v[192:195], v[16:19]
	v_mfma_f32_16x16x32_bf16 v[4:7], v[148:151], v[200:203], v[4:7]
	v_mfma_f32_16x16x32_bf16 v[0:3], v[156:159], v[200:203], v[0:3]
	s_barrier
	s_setprio 0
	s_add_i32 s92, s92, 2
	s_add_u32 s90, s90, 0x100
	s_addc_u32 s91, s91, 0
	s_cmp_gt_u32 s92, 61
	s_mov_b64 s[26:27], s[28:29]
	s_nop 0
	s_nop 0
	s_nop 0
	s_nop 0
	s_nop 0
	s_nop 0
	s_nop 0
	s_nop 0
	s_nop 0
	s_nop 0
	s_nop 0
	s_nop 0
	s_nop 0
	s_nop 0
.LBB0_852:
	ds_read_b128 v[128:131], v211
	ds_read_b128 v[132:135], v211 offset:1024
	ds_read_b128 v[136:139], v211 offset:2048
	ds_read_b128 v[140:143], v211 offset:3072
	ds_read_b128 v[144:147], v212
	ds_read_b128 v[148:151], v212 offset:1024
	ds_read_b128 v[152:155], v212 offset:2048
	ds_read_b128 v[156:159], v212 offset:3072
	s_add_u32 s28, s26, 0x100
	s_addc_u32 s29, s27, 0
	s_cmp_eq_u32 s92, 60
	s_cselect_b32 s35, s3, s29
	s_cselect_b32 s34, s17, s28
	s_cselect_b32 s31, s15, s91
	s_cselect_b32 s30, s23, s90
	v_lshl_add_u64 v[204:205], s[26:27], 0, v[180:181]
	s_add_i32 m0, s25, 0xc000
	ds_read_b128 v[160:163], v213
	ds_read_b128 v[164:167], v213 offset:1024
	ds_read_b128 v[168:171], v213 offset:2048
	ds_read_b128 v[172:175], v213 offset:3072
	ds_read_b128 v[188:191], v213 offset:4096
	ds_read_b128 v[192:195], v213 offset:5120
	ds_read_b128 v[196:199], v213 offset:6144
	ds_read_b128 v[200:203], v213 offset:7168
	global_load_lds_dwordx4 v[204:205], off
	v_lshl_add_u64 v[204:205], s[26:27], 0, v[182:183]
	s_add_i32 m0, s25, 0xe000
	s_nop 0
	global_load_lds_dwordx4 v[204:205], off
	s_waitcnt vmcnt(8)
	s_waitcnt lgkmcnt(0)
	s_setprio 1
	s_barrier
	v_mfma_f32_16x16x32_bf16 v[124:127], v[128:131], v[160:163], v[124:127]
	v_mfma_f32_16x16x32_bf16 v[120:123], v[136:139], v[160:163], v[120:123]
	v_mfma_f32_16x16x32_bf16 v[108:111], v[128:131], v[168:171], v[108:111]
	v_mfma_f32_16x16x32_bf16 v[104:107], v[136:139], v[168:171], v[104:107]
	v_mfma_f32_16x16x32_bf16 v[92:95], v[128:131], v[188:191], v[92:95]
	v_mfma_f32_16x16x32_bf16 v[88:91], v[136:139], v[188:191], v[88:91]
	v_mfma_f32_16x16x32_bf16 v[76:79], v[128:131], v[196:199], v[76:79]
	v_mfma_f32_16x16x32_bf16 v[72:75], v[136:139], v[196:199], v[72:75]
	v_mfma_f32_16x16x32_bf16 v[124:127], v[132:135], v[164:167], v[124:127]
	v_mfma_f32_16x16x32_bf16 v[120:123], v[140:143], v[164:167], v[120:123]
	v_mfma_f32_16x16x32_bf16 v[108:111], v[132:135], v[172:175], v[108:111]
	v_mfma_f32_16x16x32_bf16 v[104:107], v[140:143], v[172:175], v[104:107]
	v_mfma_f32_16x16x32_bf16 v[92:95], v[132:135], v[192:195], v[92:95]
	v_mfma_f32_16x16x32_bf16 v[88:91], v[140:143], v[192:195], v[88:91]
	v_mfma_f32_16x16x32_bf16 v[76:79], v[132:135], v[200:203], v[76:79]
	v_mfma_f32_16x16x32_bf16 v[72:75], v[140:143], v[200:203], v[72:75]
	s_setprio 0
	s_setprio 1
	v_mfma_f32_16x16x32_bf16 v[116:119], v[144:147], v[160:163], v[116:119]
	v_mfma_f32_16x16x32_bf16 v[112:115], v[152:155], v[160:163], v[112:115]
	v_mfma_f32_16x16x32_bf16 v[100:103], v[144:147], v[168:171], v[100:103]
	v_mfma_f32_16x16x32_bf16 v[96:99], v[152:155], v[168:171], v[96:99]
	v_mfma_f32_16x16x32_bf16 v[84:87], v[144:147], v[188:191], v[84:87]
	v_mfma_f32_16x16x32_bf16 v[80:83], v[152:155], v[188:191], v[80:83]
	v_mfma_f32_16x16x32_bf16 v[68:71], v[144:147], v[196:199], v[68:71]
	v_mfma_f32_16x16x32_bf16 v[64:67], v[152:155], v[196:199], v[64:67]
	v_mfma_f32_16x16x32_bf16 v[116:119], v[148:151], v[164:167], v[116:119]
	v_mfma_f32_16x16x32_bf16 v[112:115], v[156:159], v[164:167], v[112:115]
	v_mfma_f32_16x16x32_bf16 v[100:103], v[148:151], v[172:175], v[100:103]
	v_mfma_f32_16x16x32_bf16 v[96:99], v[156:159], v[172:175], v[96:99]
	v_mfma_f32_16x16x32_bf16 v[84:87], v[148:151], v[192:195], v[84:87]
	v_mfma_f32_16x16x32_bf16 v[80:83], v[156:159], v[192:195], v[80:83]
	v_mfma_f32_16x16x32_bf16 v[68:71], v[148:151], v[200:203], v[68:71]
	v_mfma_f32_16x16x32_bf16 v[64:67], v[156:159], v[200:203], v[64:67]
	s_barrier
	s_setprio 0
	s_add_i32 s26, s88, s41
	v_lshl_add_u64 v[204:205], s[30:31], 0, v[176:177]
	s_mov_b32 m0, s26
	ds_read_b128 v[160:163], v213 offset:16384
	ds_read_b128 v[164:167], v213 offset:17408
	ds_read_b128 v[168:171], v213 offset:18432
	ds_read_b128 v[172:175], v213 offset:19456
	ds_read_b128 v[188:191], v213 offset:20480
	ds_read_b128 v[192:195], v213 offset:21504
	ds_read_b128 v[196:199], v213 offset:22528
	ds_read_b128 v[200:203], v213 offset:23552
	global_load_lds_dwordx4 v[204:205], off
	s_add_i32 m0, s26, 0x2000
	s_add_u32 s26, s30, 0x100000
	v_lshl_add_u64 v[216:217], s[30:31], 0, v[178:179]
	s_addc_u32 s27, s31, 0
	s_add_i32 s93, s89, s41
	global_load_lds_dwordx4 v[216:217], off
	v_lshl_add_u64 v[218:219], s[26:27], 0, v[176:177]
	s_mov_b32 m0, s93
	v_lshl_add_u64 v[220:221], s[34:35], 0, v[178:179]
	global_load_lds_dwordx4 v[218:219], off
	v_lshl_add_u64 v[218:219], s[26:27], 0, v[178:179]
	s_add_i32 m0, s93, 0x2000
	s_nop 0
	global_load_lds_dwordx4 v[218:219], off
	v_lshl_add_u64 v[218:219], s[34:35], 0, v[176:177]
	s_mov_b32 m0, s25
	s_nop 0
	global_load_lds_dwordx4 v[218:219], off
	s_mov_b32 m0, s50
	s_nop 0
	global_load_lds_dwordx4 v[220:221], off
	s_waitcnt vmcnt(8)
	s_waitcnt lgkmcnt(0)
	s_setprio 1
	s_barrier
	v_mfma_f32_16x16x32_bf16 v[60:63], v[128:131], v[160:163], v[60:63]
	v_mfma_f32_16x16x32_bf16 v[56:59], v[136:139], v[160:163], v[56:59]
	v_mfma_f32_16x16x32_bf16 v[44:47], v[128:131], v[168:171], v[44:47]
	v_mfma_f32_16x16x32_bf16 v[40:43], v[136:139], v[168:171], v[40:43]
	v_mfma_f32_16x16x32_bf16 v[28:31], v[128:131], v[188:191], v[28:31]
	v_mfma_f32_16x16x32_bf16 v[24:27], v[136:139], v[188:191], v[24:27]
	v_mfma_f32_16x16x32_bf16 v[12:15], v[128:131], v[196:199], v[12:15]
	v_mfma_f32_16x16x32_bf16 v[8:11], v[136:139], v[196:199], v[8:11]
	v_mfma_f32_16x16x32_bf16 v[60:63], v[132:135], v[164:167], v[60:63]
	v_mfma_f32_16x16x32_bf16 v[56:59], v[140:143], v[164:167], v[56:59]
	v_mfma_f32_16x16x32_bf16 v[44:47], v[132:135], v[172:175], v[44:47]
	v_mfma_f32_16x16x32_bf16 v[40:43], v[140:143], v[172:175], v[40:43]
	v_mfma_f32_16x16x32_bf16 v[28:31], v[132:135], v[192:195], v[28:31]
	v_mfma_f32_16x16x32_bf16 v[24:27], v[140:143], v[192:195], v[24:27]
	v_mfma_f32_16x16x32_bf16 v[12:15], v[132:135], v[200:203], v[12:15]
	v_mfma_f32_16x16x32_bf16 v[8:11], v[140:143], v[200:203], v[8:11]
	s_setprio 0
	s_setprio 1
	v_mfma_f32_16x16x32_bf16 v[52:55], v[144:147], v[160:163], v[52:55]
	v_mfma_f32_16x16x32_bf16 v[48:51], v[152:155], v[160:163], v[48:51]
	v_mfma_f32_16x16x32_bf16 v[36:39], v[144:147], v[168:171], v[36:39]
	v_mfma_f32_16x16x32_bf16 v[32:35], v[152:155], v[168:171], v[32:35]
	v_mfma_f32_16x16x32_bf16 v[20:23], v[144:147], v[188:191], v[20:23]
	v_mfma_f32_16x16x32_bf16 v[16:19], v[152:155], v[188:191], v[16:19]
	v_mfma_f32_16x16x32_bf16 v[4:7], v[144:147], v[196:199], v[4:7]
	v_mfma_f32_16x16x32_bf16 v[0:3], v[152:155], v[196:199], v[0:3]
	v_mfma_f32_16x16x32_bf16 v[52:55], v[148:151], v[164:167], v[52:55]
	v_mfma_f32_16x16x32_bf16 v[48:51], v[156:159], v[164:167], v[48:51]
	v_mfma_f32_16x16x32_bf16 v[36:39], v[148:151], v[172:175], v[36:39]
	v_mfma_f32_16x16x32_bf16 v[32:35], v[156:159], v[172:175], v[32:35]
	v_mfma_f32_16x16x32_bf16 v[20:23], v[148:151], v[192:195], v[20:23]
	v_mfma_f32_16x16x32_bf16 v[16:19], v[156:159], v[192:195], v[16:19]
	v_mfma_f32_16x16x32_bf16 v[4:7], v[148:151], v[200:203], v[4:7]
	v_mfma_f32_16x16x32_bf16 v[0:3], v[156:159], v[200:203], v[0:3]
	s_barrier
	s_setprio 0
	s_add_i32 s93, 0, 0x18000
	s_add_i32 s94, 0, 0x1c000
	v_add_u32_e32 v140, s93, v209
	v_add_u32_e32 v156, s94, v209
	ds_read_b128 v[128:131], v140
	ds_read_b128 v[132:135], v140 offset:1024
	ds_read_b128 v[136:139], v140 offset:2048
	ds_read_b128 v[140:143], v140 offset:3072
	ds_read_b128 v[144:147], v156
	ds_read_b128 v[148:151], v156 offset:1024
	ds_read_b128 v[152:155], v156 offset:2048
	ds_read_b128 v[156:159], v156 offset:3072
	s_add_u32 s26, s34, 0x100000
	s_addc_u32 s27, s35, 0
	s_mov_b32 m0, s51
	v_lshl_add_u64 v[222:223], s[26:27], 0, v[176:177]
	ds_read_b128 v[160:163], v213 offset:32768
	ds_read_b128 v[164:167], v213 offset:33792
	ds_read_b128 v[168:171], v213 offset:34816
	ds_read_b128 v[172:175], v213 offset:35840
	ds_read_b128 v[188:191], v213 offset:36864
	ds_read_b128 v[192:195], v213 offset:37888
	ds_read_b128 v[196:199], v213 offset:38912
	ds_read_b128 v[200:203], v213 offset:39936
	global_load_lds_dwordx4 v[222:223], off
	v_lshl_add_u64 v[222:223], s[26:27], 0, v[178:179]
	s_mov_b32 m0, s76
	s_nop 0
	global_load_lds_dwordx4 v[222:223], off
	s_waitcnt vmcnt(8)
	s_waitcnt lgkmcnt(0)
	s_setprio 1
	s_barrier
	v_mfma_f32_16x16x32_bf16 v[124:127], v[128:131], v[160:163], v[124:127]
	v_mfma_f32_16x16x32_bf16 v[120:123], v[136:139], v[160:163], v[120:123]
	v_mfma_f32_16x16x32_bf16 v[108:111], v[128:131], v[168:171], v[108:111]
	v_mfma_f32_16x16x32_bf16 v[104:107], v[136:139], v[168:171], v[104:107]
	v_mfma_f32_16x16x32_bf16 v[92:95], v[128:131], v[188:191], v[92:95]
	v_mfma_f32_16x16x32_bf16 v[88:91], v[136:139], v[188:191], v[88:91]
	v_mfma_f32_16x16x32_bf16 v[76:79], v[128:131], v[196:199], v[76:79]
	v_mfma_f32_16x16x32_bf16 v[72:75], v[136:139], v[196:199], v[72:75]
	v_mfma_f32_16x16x32_bf16 v[124:127], v[132:135], v[164:167], v[124:127]
	v_mfma_f32_16x16x32_bf16 v[120:123], v[140:143], v[164:167], v[120:123]
	v_mfma_f32_16x16x32_bf16 v[108:111], v[132:135], v[172:175], v[108:111]
	v_mfma_f32_16x16x32_bf16 v[104:107], v[140:143], v[172:175], v[104:107]
	v_mfma_f32_16x16x32_bf16 v[92:95], v[132:135], v[192:195], v[92:95]
	v_mfma_f32_16x16x32_bf16 v[88:91], v[140:143], v[192:195], v[88:91]
	v_mfma_f32_16x16x32_bf16 v[76:79], v[132:135], v[200:203], v[76:79]
	v_mfma_f32_16x16x32_bf16 v[72:75], v[140:143], v[200:203], v[72:75]
	s_setprio 0
	s_setprio 1
	v_mfma_f32_16x16x32_bf16 v[116:119], v[144:147], v[160:163], v[116:119]
	v_mfma_f32_16x16x32_bf16 v[112:115], v[152:155], v[160:163], v[112:115]
	v_mfma_f32_16x16x32_bf16 v[100:103], v[144:147], v[168:171], v[100:103]
	v_mfma_f32_16x16x32_bf16 v[96:99], v[152:155], v[168:171], v[96:99]
	v_mfma_f32_16x16x32_bf16 v[84:87], v[144:147], v[188:191], v[84:87]
	v_mfma_f32_16x16x32_bf16 v[80:83], v[152:155], v[188:191], v[80:83]
	v_mfma_f32_16x16x32_bf16 v[68:71], v[144:147], v[196:199], v[68:71]
	v_mfma_f32_16x16x32_bf16 v[64:67], v[152:155], v[196:199], v[64:67]
	v_mfma_f32_16x16x32_bf16 v[116:119], v[148:151], v[164:167], v[116:119]
	v_mfma_f32_16x16x32_bf16 v[112:115], v[156:159], v[164:167], v[112:115]
	v_mfma_f32_16x16x32_bf16 v[100:103], v[148:151], v[172:175], v[100:103]
	v_mfma_f32_16x16x32_bf16 v[96:99], v[156:159], v[172:175], v[96:99]
	v_mfma_f32_16x16x32_bf16 v[84:87], v[148:151], v[192:195], v[84:87]
	v_mfma_f32_16x16x32_bf16 v[80:83], v[156:159], v[192:195], v[80:83]
	v_mfma_f32_16x16x32_bf16 v[68:71], v[148:151], v[200:203], v[68:71]
	v_mfma_f32_16x16x32_bf16 v[64:67], v[156:159], v[200:203], v[64:67]
	s_barrier
	s_setprio 0
	s_add_i32 s26, s93, s41
	v_lshl_add_u64 v[204:205], v[204:205], 0, s[10:11]
	s_mov_b32 m0, s26
	ds_read_b128 v[160:163], v213 offset:49152
	ds_read_b128 v[164:167], v213 offset:50176
	ds_read_b128 v[168:171], v213 offset:51200
	ds_read_b128 v[172:175], v213 offset:52224
	ds_read_b128 v[188:191], v213 offset:53248
	ds_read_b128 v[192:195], v213 offset:54272
	ds_read_b128 v[196:199], v213 offset:55296
	ds_read_b128 v[200:203], v213 offset:56320
	global_load_lds_dwordx4 v[204:205], off
	s_add_i32 m0, s26, 0x2000
	s_add_u32 s26, s30, 0x100080
	v_lshl_add_u64 v[204:205], v[216:217], 0, s[10:11]
	s_addc_u32 s27, s31, 0
	s_add_i32 s30, s94, s41
	global_load_lds_dwordx4 v[204:205], off
	v_lshl_add_u64 v[204:205], s[26:27], 0, v[176:177]
	s_mov_b32 m0, s30
	s_nop 0
	global_load_lds_dwordx4 v[204:205], off
	v_lshl_add_u64 v[204:205], s[26:27], 0, v[178:179]
	s_add_i32 m0, s30, 0x2000
	s_nop 0
	global_load_lds_dwordx4 v[204:205], off
	v_lshl_add_u64 v[204:205], v[218:219], 0, s[10:11]
	s_mov_b32 m0, s78
	s_nop 0
	global_load_lds_dwordx4 v[204:205], off
	v_lshl_add_u64 v[204:205], v[220:221], 0, s[10:11]
	s_mov_b32 m0, s79
	s_nop 0
	global_load_lds_dwordx4 v[204:205], off
	s_waitcnt vmcnt(8)
	s_waitcnt lgkmcnt(0)
	s_setprio 1
	s_barrier
	v_mfma_f32_16x16x32_bf16 v[60:63], v[128:131], v[160:163], v[60:63]
	v_mfma_f32_16x16x32_bf16 v[56:59], v[136:139], v[160:163], v[56:59]
	v_mfma_f32_16x16x32_bf16 v[44:47], v[128:131], v[168:171], v[44:47]
	v_mfma_f32_16x16x32_bf16 v[40:43], v[136:139], v[168:171], v[40:43]
	v_mfma_f32_16x16x32_bf16 v[28:31], v[128:131], v[188:191], v[28:31]
	v_mfma_f32_16x16x32_bf16 v[24:27], v[136:139], v[188:191], v[24:27]
	v_mfma_f32_16x16x32_bf16 v[12:15], v[128:131], v[196:199], v[12:15]
	v_mfma_f32_16x16x32_bf16 v[8:11], v[136:139], v[196:199], v[8:11]
	v_mfma_f32_16x16x32_bf16 v[60:63], v[132:135], v[164:167], v[60:63]
	v_mfma_f32_16x16x32_bf16 v[56:59], v[140:143], v[164:167], v[56:59]
	v_mfma_f32_16x16x32_bf16 v[44:47], v[132:135], v[172:175], v[44:47]
	v_mfma_f32_16x16x32_bf16 v[40:43], v[140:143], v[172:175], v[40:43]
	v_mfma_f32_16x16x32_bf16 v[28:31], v[132:135], v[192:195], v[28:31]
	v_mfma_f32_16x16x32_bf16 v[24:27], v[140:143], v[192:195], v[24:27]
	v_mfma_f32_16x16x32_bf16 v[12:15], v[132:135], v[200:203], v[12:15]
	v_mfma_f32_16x16x32_bf16 v[8:11], v[140:143], v[200:203], v[8:11]
	s_setprio 0
	s_setprio 1
	v_mfma_f32_16x16x32_bf16 v[52:55], v[144:147], v[160:163], v[52:55]
	v_mfma_f32_16x16x32_bf16 v[48:51], v[152:155], v[160:163], v[48:51]
	v_mfma_f32_16x16x32_bf16 v[36:39], v[144:147], v[168:171], v[36:39]
	v_mfma_f32_16x16x32_bf16 v[32:35], v[152:155], v[168:171], v[32:35]
	v_mfma_f32_16x16x32_bf16 v[20:23], v[144:147], v[188:191], v[20:23]
	v_mfma_f32_16x16x32_bf16 v[16:19], v[152:155], v[188:191], v[16:19]
	v_mfma_f32_16x16x32_bf16 v[4:7], v[144:147], v[196:199], v[4:7]
	v_mfma_f32_16x16x32_bf16 v[0:3], v[152:155], v[196:199], v[0:3]
	v_mfma_f32_16x16x32_bf16 v[52:55], v[148:151], v[164:167], v[52:55]
	v_mfma_f32_16x16x32_bf16 v[48:51], v[156:159], v[164:167], v[48:51]
	v_mfma_f32_16x16x32_bf16 v[36:39], v[148:151], v[172:175], v[36:39]
	v_mfma_f32_16x16x32_bf16 v[32:35], v[156:159], v[172:175], v[32:35]
	v_mfma_f32_16x16x32_bf16 v[20:23], v[148:151], v[192:195], v[20:23]
	v_mfma_f32_16x16x32_bf16 v[16:19], v[156:159], v[192:195], v[16:19]
	v_mfma_f32_16x16x32_bf16 v[4:7], v[148:151], v[200:203], v[4:7]
	v_mfma_f32_16x16x32_bf16 v[0:3], v[156:159], v[200:203], v[0:3]
	s_barrier
	s_setprio 0
	s_add_i32 s92, s92, 2
	s_add_u32 s90, s90, 0x100
	s_addc_u32 s91, s91, 0
	s_cmp_gt_u32 s92, 61
	s_mov_b64 s[26:27], s[28:29]
	s_cbranch_scc0 .LBB0_852
	s_nop 0
	s_nop 0
	s_and_b64 vcc, exec, s[12:13]
	s_cbranch_vccz .LBB0_855
	s_barrier

.LBB0_1388:
	s_ashr_i32 s19, s18, 31
	s_lshl_b64 s[20:21], s[18:19], 21
	s_add_u32 s20, s80, s20
	s_addc_u32 s21, s81, s21
	s_and_b64 s[22:23], s[4:5], exec
	s_cselect_b32 s3, s21, s29
	s_cselect_b32 s19, s20, s28
	s_ashr_i32 s17, s16, 31
	s_lshl_b64 s[22:23], s[16:17], 21
	s_add_u32 s22, s33, s22
	s_addc_u32 s23, s52, s23
	s_and_b64 s[34:35], s[4:5], exec
	s_cselect_b32 s17, s23, s31
	s_cselect_b32 s25, s22, s30
	s_add_u32 s54, s30, 0x100
	s_addc_u32 s55, s31, 0
	s_mov_b32 s56, -2
	s_waitcnt lgkmcnt(0)
	ds_read_b128 v[128:131], v212
	ds_read_b128 v[132:135], v212 offset:1024
	ds_read_b128 v[136:139], v212 offset:2048
	ds_read_b128 v[140:143], v212 offset:3072
	ds_read_b128 v[144:147], v213
	ds_read_b128 v[148:151], v213 offset:1024
	ds_read_b128 v[152:155], v213 offset:2048
	ds_read_b128 v[156:159], v213 offset:3072
	s_add_u32 s30, s28, 0x100
	s_addc_u32 s31, s29, 0
	s_cmp_eq_u32 s56, 60
	s_cselect_b32 s37, s3, s31
	s_cselect_b32 s36, s19, s30
	s_cselect_b32 s35, s17, s55
	s_cselect_b32 s34, s25, s54
	v_lshl_add_u64 v[204:205], s[28:29], 0, v[180:181]
	s_add_i32 m0, s27, 0xc000
	ds_read_b128 v[160:163], v214
	ds_read_b128 v[164:167], v214 offset:1024
	ds_read_b128 v[168:171], v214 offset:2048
	ds_read_b128 v[172:175], v214 offset:3072
	ds_read_b128 v[188:191], v214 offset:4096
	ds_read_b128 v[192:195], v214 offset:5120
	ds_read_b128 v[196:199], v214 offset:6144
	ds_read_b128 v[200:203], v214 offset:7168
	global_load_lds_dwordx4 v[204:205], off
	v_lshl_add_u64 v[204:205], s[28:29], 0, v[182:183]
	s_add_i32 m0, s27, 0xe000
	s_nop 0
	global_load_lds_dwordx4 v[204:205], off
	s_waitcnt vmcnt(8)
	s_waitcnt lgkmcnt(0)
	s_setprio 1
	s_barrier
	v_mfma_f32_16x16x32_bf16 v[124:127], v[128:131], v[160:163], 0
	v_mfma_f32_16x16x32_bf16 v[120:123], v[136:139], v[160:163], 0
	v_mfma_f32_16x16x32_bf16 v[108:111], v[128:131], v[168:171], 0
	v_mfma_f32_16x16x32_bf16 v[104:107], v[136:139], v[168:171], 0
	v_mfma_f32_16x16x32_bf16 v[92:95], v[128:131], v[188:191], 0
	v_mfma_f32_16x16x32_bf16 v[88:91], v[136:139], v[188:191], 0
	v_mfma_f32_16x16x32_bf16 v[76:79], v[128:131], v[196:199], 0
	v_mfma_f32_16x16x32_bf16 v[72:75], v[136:139], v[196:199], 0
	v_mfma_f32_16x16x32_bf16 v[124:127], v[132:135], v[164:167], v[124:127]
	v_mfma_f32_16x16x32_bf16 v[120:123], v[140:143], v[164:167], v[120:123]
	v_mfma_f32_16x16x32_bf16 v[108:111], v[132:135], v[172:175], v[108:111]
	v_mfma_f32_16x16x32_bf16 v[104:107], v[140:143], v[172:175], v[104:107]
	v_mfma_f32_16x16x32_bf16 v[92:95], v[132:135], v[192:195], v[92:95]
	v_mfma_f32_16x16x32_bf16 v[88:91], v[140:143], v[192:195], v[88:91]
	v_mfma_f32_16x16x32_bf16 v[76:79], v[132:135], v[200:203], v[76:79]
	v_mfma_f32_16x16x32_bf16 v[72:75], v[140:143], v[200:203], v[72:75]
	s_setprio 0
	s_setprio 1
	v_mfma_f32_16x16x32_bf16 v[116:119], v[144:147], v[160:163], 0
	v_mfma_f32_16x16x32_bf16 v[112:115], v[152:155], v[160:163], 0
	v_mfma_f32_16x16x32_bf16 v[100:103], v[144:147], v[168:171], 0
	v_mfma_f32_16x16x32_bf16 v[96:99], v[152:155], v[168:171], 0
	v_mfma_f32_16x16x32_bf16 v[84:87], v[144:147], v[188:191], 0
	v_mfma_f32_16x16x32_bf16 v[80:83], v[152:155], v[188:191], 0
	v_mfma_f32_16x16x32_bf16 v[68:71], v[144:147], v[196:199], 0
	v_mfma_f32_16x16x32_bf16 v[64:67], v[152:155], v[196:199], 0
	v_mfma_f32_16x16x32_bf16 v[116:119], v[148:151], v[164:167], v[116:119]
	v_mfma_f32_16x16x32_bf16 v[112:115], v[156:159], v[164:167], v[112:115]
	v_mfma_f32_16x16x32_bf16 v[100:103], v[148:151], v[172:175], v[100:103]
	v_mfma_f32_16x16x32_bf16 v[96:99], v[156:159], v[172:175], v[96:99]
	v_mfma_f32_16x16x32_bf16 v[84:87], v[148:151], v[192:195], v[84:87]
	v_mfma_f32_16x16x32_bf16 v[80:83], v[156:159], v[192:195], v[80:83]
	v_mfma_f32_16x16x32_bf16 v[68:71], v[148:151], v[200:203], v[68:71]
	v_mfma_f32_16x16x32_bf16 v[64:67], v[156:159], v[200:203], v[64:67]
	s_barrier
	s_setprio 0
	s_add_i32 s28, s51, s40
	v_lshl_add_u64 v[204:205], s[34:35], 0, v[176:177]
	s_mov_b32 m0, s28
	ds_read_b128 v[160:163], v214 offset:16384
	ds_read_b128 v[164:167], v214 offset:17408
	ds_read_b128 v[168:171], v214 offset:18432
	ds_read_b128 v[172:175], v214 offset:19456
	ds_read_b128 v[188:191], v214 offset:20480
	ds_read_b128 v[192:195], v214 offset:21504
	ds_read_b128 v[196:199], v214 offset:22528
	ds_read_b128 v[200:203], v214 offset:23552
	global_load_lds_dwordx4 v[204:205], off
	s_add_i32 m0, s28, 0x2000
	s_add_u32 s28, s34, 0x100000
	v_lshl_add_u64 v[216:217], s[34:35], 0, v[178:179]
	s_addc_u32 s29, s35, 0
	s_add_i32 s57, s53, s40
	global_load_lds_dwordx4 v[216:217], off
	v_lshl_add_u64 v[218:219], s[28:29], 0, v[176:177]
	s_mov_b32 m0, s57
	v_lshl_add_u64 v[220:221], s[36:37], 0, v[178:179]
	global_load_lds_dwordx4 v[218:219], off
	v_lshl_add_u64 v[218:219], s[28:29], 0, v[178:179]
	s_add_i32 m0, s57, 0x2000
	s_nop 0
	global_load_lds_dwordx4 v[218:219], off
	v_lshl_add_u64 v[218:219], s[36:37], 0, v[176:177]
	s_mov_b32 m0, s27
	s_nop 0
	global_load_lds_dwordx4 v[218:219], off
	s_mov_b32 m0, s41
	s_nop 0
	global_load_lds_dwordx4 v[220:221], off
	s_waitcnt vmcnt(8)
	s_waitcnt lgkmcnt(0)
	s_setprio 1
	s_barrier
	v_mfma_f32_16x16x32_bf16 v[60:63], v[128:131], v[160:163], 0
	v_mfma_f32_16x16x32_bf16 v[56:59], v[136:139], v[160:163], 0
	v_mfma_f32_16x16x32_bf16 v[44:47], v[128:131], v[168:171], 0
	v_mfma_f32_16x16x32_bf16 v[40:43], v[136:139], v[168:171], 0
	v_mfma_f32_16x16x32_bf16 v[28:31], v[128:131], v[188:191], 0
	v_mfma_f32_16x16x32_bf16 v[24:27], v[136:139], v[188:191], 0
	v_mfma_f32_16x16x32_bf16 v[12:15], v[128:131], v[196:199], 0
	v_mfma_f32_16x16x32_bf16 v[8:11], v[136:139], v[196:199], 0
	v_mfma_f32_16x16x32_bf16 v[60:63], v[132:135], v[164:167], v[60:63]
	v_mfma_f32_16x16x32_bf16 v[56:59], v[140:143], v[164:167], v[56:59]
	v_mfma_f32_16x16x32_bf16 v[44:47], v[132:135], v[172:175], v[44:47]
	v_mfma_f32_16x16x32_bf16 v[40:43], v[140:143], v[172:175], v[40:43]
	v_mfma_f32_16x16x32_bf16 v[28:31], v[132:135], v[192:195], v[28:31]
	v_mfma_f32_16x16x32_bf16 v[24:27], v[140:143], v[192:195], v[24:27]
	v_mfma_f32_16x16x32_bf16 v[12:15], v[132:135], v[200:203], v[12:15]
	v_mfma_f32_16x16x32_bf16 v[8:11], v[140:143], v[200:203], v[8:11]
	s_setprio 0
	s_setprio 1
	v_mfma_f32_16x16x32_bf16 v[52:55], v[144:147], v[160:163], 0
	v_mfma_f32_16x16x32_bf16 v[48:51], v[152:155], v[160:163], 0
	v_mfma_f32_16x16x32_bf16 v[36:39], v[144:147], v[168:171], 0
	v_mfma_f32_16x16x32_bf16 v[32:35], v[152:155], v[168:171], 0
	v_mfma_f32_16x16x32_bf16 v[20:23], v[144:147], v[188:191], 0
	v_mfma_f32_16x16x32_bf16 v[16:19], v[152:155], v[188:191], 0
	v_mfma_f32_16x16x32_bf16 v[4:7], v[144:147], v[196:199], 0
	v_mfma_f32_16x16x32_bf16 v[0:3], v[152:155], v[196:199], 0
	v_mfma_f32_16x16x32_bf16 v[52:55], v[148:151], v[164:167], v[52:55]
	v_mfma_f32_16x16x32_bf16 v[48:51], v[156:159], v[164:167], v[48:51]
	v_mfma_f32_16x16x32_bf16 v[36:39], v[148:151], v[172:175], v[36:39]
	v_mfma_f32_16x16x32_bf16 v[32:35], v[156:159], v[172:175], v[32:35]
	v_mfma_f32_16x16x32_bf16 v[20:23], v[148:151], v[192:195], v[20:23]
	v_mfma_f32_16x16x32_bf16 v[16:19], v[156:159], v[192:195], v[16:19]
	v_mfma_f32_16x16x32_bf16 v[4:7], v[148:151], v[200:203], v[4:7]
	v_mfma_f32_16x16x32_bf16 v[0:3], v[156:159], v[200:203], v[0:3]
	s_barrier
	s_setprio 0
	s_add_i32 s57, 0, 0x18000
	s_add_i32 s58, 0, 0x1c000
	v_add_u32_e32 v140, s57, v210
	v_add_u32_e32 v156, s58, v210
	ds_read_b128 v[128:131], v140
	ds_read_b128 v[132:135], v140 offset:1024
	ds_read_b128 v[136:139], v140 offset:2048
	ds_read_b128 v[140:143], v140 offset:3072
	ds_read_b128 v[144:147], v156
	ds_read_b128 v[148:151], v156 offset:1024
	ds_read_b128 v[152:155], v156 offset:2048
	ds_read_b128 v[156:159], v156 offset:3072
	s_add_u32 s28, s36, 0x100000
	s_addc_u32 s29, s37, 0
	s_mov_b32 m0, s42
	v_lshl_add_u64 v[222:223], s[28:29], 0, v[176:177]
	ds_read_b128 v[160:163], v214 offset:32768
	ds_read_b128 v[164:167], v214 offset:33792
	ds_read_b128 v[168:171], v214 offset:34816
	ds_read_b128 v[172:175], v214 offset:35840
	ds_read_b128 v[188:191], v214 offset:36864
	ds_read_b128 v[192:195], v214 offset:37888
	ds_read_b128 v[196:199], v214 offset:38912
	ds_read_b128 v[200:203], v214 offset:39936
	global_load_lds_dwordx4 v[222:223], off
	v_lshl_add_u64 v[222:223], s[28:29], 0, v[178:179]
	s_mov_b32 m0, s43
	s_nop 0
	global_load_lds_dwordx4 v[222:223], off
	s_waitcnt vmcnt(8)
	s_waitcnt lgkmcnt(0)
	s_setprio 1
	s_barrier
	v_mfma_f32_16x16x32_bf16 v[124:127], v[128:131], v[160:163], v[124:127]
	v_mfma_f32_16x16x32_bf16 v[120:123], v[136:139], v[160:163], v[120:123]
	v_mfma_f32_16x16x32_bf16 v[108:111], v[128:131], v[168:171], v[108:111]
	v_mfma_f32_16x16x32_bf16 v[104:107], v[136:139], v[168:171], v[104:107]
	v_mfma_f32_16x16x32_bf16 v[92:95], v[128:131], v[188:191], v[92:95]
	v_mfma_f32_16x16x32_bf16 v[88:91], v[136:139], v[188:191], v[88:91]
	v_mfma_f32_16x16x32_bf16 v[76:79], v[128:131], v[196:199], v[76:79]
	v_mfma_f32_16x16x32_bf16 v[72:75], v[136:139], v[196:199], v[72:75]
	v_mfma_f32_16x16x32_bf16 v[124:127], v[132:135], v[164:167], v[124:127]
	v_mfma_f32_16x16x32_bf16 v[120:123], v[140:143], v[164:167], v[120:123]
	v_mfma_f32_16x16x32_bf16 v[108:111], v[132:135], v[172:175], v[108:111]
	v_mfma_f32_16x16x32_bf16 v[104:107], v[140:143], v[172:175], v[104:107]
	v_mfma_f32_16x16x32_bf16 v[92:95], v[132:135], v[192:195], v[92:95]
	v_mfma_f32_16x16x32_bf16 v[88:91], v[140:143], v[192:195], v[88:91]
	v_mfma_f32_16x16x32_bf16 v[76:79], v[132:135], v[200:203], v[76:79]
	v_mfma_f32_16x16x32_bf16 v[72:75], v[140:143], v[200:203], v[72:75]
	s_setprio 0
	s_setprio 1
	v_mfma_f32_16x16x32_bf16 v[116:119], v[144:147], v[160:163], v[116:119]
	v_mfma_f32_16x16x32_bf16 v[112:115], v[152:155], v[160:163], v[112:115]
	v_mfma_f32_16x16x32_bf16 v[100:103], v[144:147], v[168:171], v[100:103]
	v_mfma_f32_16x16x32_bf16 v[96:99], v[152:155], v[168:171], v[96:99]
	v_mfma_f32_16x16x32_bf16 v[84:87], v[144:147], v[188:191], v[84:87]
	v_mfma_f32_16x16x32_bf16 v[80:83], v[152:155], v[188:191], v[80:83]
	v_mfma_f32_16x16x32_bf16 v[68:71], v[144:147], v[196:199], v[68:71]
	v_mfma_f32_16x16x32_bf16 v[64:67], v[152:155], v[196:199], v[64:67]
	v_mfma_f32_16x16x32_bf16 v[116:119], v[148:151], v[164:167], v[116:119]
	v_mfma_f32_16x16x32_bf16 v[112:115], v[156:159], v[164:167], v[112:115]
	v_mfma_f32_16x16x32_bf16 v[100:103], v[148:151], v[172:175], v[100:103]
	v_mfma_f32_16x16x32_bf16 v[96:99], v[156:159], v[172:175], v[96:99]
	v_mfma_f32_16x16x32_bf16 v[84:87], v[148:151], v[192:195], v[84:87]
	v_mfma_f32_16x16x32_bf16 v[80:83], v[156:159], v[192:195], v[80:83]
	v_mfma_f32_16x16x32_bf16 v[68:71], v[148:151], v[200:203], v[68:71]
	v_mfma_f32_16x16x32_bf16 v[64:67], v[156:159], v[200:203], v[64:67]
	s_barrier
	s_setprio 0
	s_add_i32 s28, s57, s40
	v_lshl_add_u64 v[204:205], v[204:205], 0, s[12:13]
	s_mov_b32 m0, s28
	ds_read_b128 v[160:163], v214 offset:49152
	ds_read_b128 v[164:167], v214 offset:50176
	ds_read_b128 v[168:171], v214 offset:51200
	ds_read_b128 v[172:175], v214 offset:52224
	ds_read_b128 v[188:191], v214 offset:53248
	ds_read_b128 v[192:195], v214 offset:54272
	ds_read_b128 v[196:199], v214 offset:55296
	ds_read_b128 v[200:203], v214 offset:56320
	global_load_lds_dwordx4 v[204:205], off
	s_add_i32 m0, s28, 0x2000
	s_add_u32 s28, s34, 0x100080
	v_lshl_add_u64 v[204:205], v[216:217], 0, s[12:13]
	s_addc_u32 s29, s35, 0
	s_add_i32 s34, s58, s40
	global_load_lds_dwordx4 v[204:205], off
	v_lshl_add_u64 v[204:205], s[28:29], 0, v[176:177]
	s_mov_b32 m0, s34
	s_nop 0
	global_load_lds_dwordx4 v[204:205], off
	v_lshl_add_u64 v[204:205], s[28:29], 0, v[178:179]
	s_add_i32 m0, s34, 0x2000
	s_nop 0
	global_load_lds_dwordx4 v[204:205], off
	v_lshl_add_u64 v[204:205], v[218:219], 0, s[12:13]
	s_mov_b32 m0, s45
	s_nop 0
	global_load_lds_dwordx4 v[204:205], off
	v_lshl_add_u64 v[204:205], v[220:221], 0, s[12:13]
	s_mov_b32 m0, s48
	s_nop 0
	global_load_lds_dwordx4 v[204:205], off
	s_waitcnt vmcnt(8)
	s_waitcnt lgkmcnt(0)
	s_setprio 1
	s_barrier
	v_mfma_f32_16x16x32_bf16 v[60:63], v[128:131], v[160:163], v[60:63]
	v_mfma_f32_16x16x32_bf16 v[56:59], v[136:139], v[160:163], v[56:59]
	v_mfma_f32_16x16x32_bf16 v[44:47], v[128:131], v[168:171], v[44:47]
	v_mfma_f32_16x16x32_bf16 v[40:43], v[136:139], v[168:171], v[40:43]
	v_mfma_f32_16x16x32_bf16 v[28:31], v[128:131], v[188:191], v[28:31]
	v_mfma_f32_16x16x32_bf16 v[24:27], v[136:139], v[188:191], v[24:27]
	v_mfma_f32_16x16x32_bf16 v[12:15], v[128:131], v[196:199], v[12:15]
	v_mfma_f32_16x16x32_bf16 v[8:11], v[136:139], v[196:199], v[8:11]
	v_mfma_f32_16x16x32_bf16 v[60:63], v[132:135], v[164:167], v[60:63]
	v_mfma_f32_16x16x32_bf16 v[56:59], v[140:143], v[164:167], v[56:59]
	v_mfma_f32_16x16x32_bf16 v[44:47], v[132:135], v[172:175], v[44:47]
	v_mfma_f32_16x16x32_bf16 v[40:43], v[140:143], v[172:175], v[40:43]
	v_mfma_f32_16x16x32_bf16 v[28:31], v[132:135], v[192:195], v[28:31]
	v_mfma_f32_16x16x32_bf16 v[24:27], v[140:143], v[192:195], v[24:27]
	v_mfma_f32_16x16x32_bf16 v[12:15], v[132:135], v[200:203], v[12:15]
	v_mfma_f32_16x16x32_bf16 v[8:11], v[140:143], v[200:203], v[8:11]
	s_setprio 0
	s_setprio 1
	v_mfma_f32_16x16x32_bf16 v[52:55], v[144:147], v[160:163], v[52:55]
	v_mfma_f32_16x16x32_bf16 v[48:51], v[152:155], v[160:163], v[48:51]
	v_mfma_f32_16x16x32_bf16 v[36:39], v[144:147], v[168:171], v[36:39]
	v_mfma_f32_16x16x32_bf16 v[32:35], v[152:155], v[168:171], v[32:35]
	v_mfma_f32_16x16x32_bf16 v[20:23], v[144:147], v[188:191], v[20:23]
	v_mfma_f32_16x16x32_bf16 v[16:19], v[152:155], v[188:191], v[16:19]
	v_mfma_f32_16x16x32_bf16 v[4:7], v[144:147], v[196:199], v[4:7]
	v_mfma_f32_16x16x32_bf16 v[0:3], v[152:155], v[196:199], v[0:3]
	v_mfma_f32_16x16x32_bf16 v[52:55], v[148:151], v[164:167], v[52:55]
	v_mfma_f32_16x16x32_bf16 v[48:51], v[156:159], v[164:167], v[48:51]
	v_mfma_f32_16x16x32_bf16 v[36:39], v[148:151], v[172:175], v[36:39]
	v_mfma_f32_16x16x32_bf16 v[32:35], v[156:159], v[172:175], v[32:35]
	v_mfma_f32_16x16x32_bf16 v[20:23], v[148:151], v[192:195], v[20:23]
	v_mfma_f32_16x16x32_bf16 v[16:19], v[156:159], v[192:195], v[16:19]
	v_mfma_f32_16x16x32_bf16 v[4:7], v[148:151], v[200:203], v[4:7]
	v_mfma_f32_16x16x32_bf16 v[0:3], v[156:159], v[200:203], v[0:3]
	s_barrier
	s_setprio 0
	s_add_i32 s56, s56, 2
	s_add_u32 s54, s54, 0x100
	s_addc_u32 s55, s55, 0
	s_cmp_gt_u32 s56, 61
	s_mov_b64 s[28:29], s[30:31]
	s_nop 0
	s_nop 0
	s_nop 0
	s_nop 0
	s_nop 0
	s_nop 0
	s_nop 0
	s_nop 0
	s_nop 0
	s_nop 0
	s_nop 0
	s_nop 0
	s_nop 0
.LBB0_1389:
	ds_read_b128 v[128:131], v212
	ds_read_b128 v[132:135], v212 offset:1024
	ds_read_b128 v[136:139], v212 offset:2048
	ds_read_b128 v[140:143], v212 offset:3072
	ds_read_b128 v[144:147], v213
	ds_read_b128 v[148:151], v213 offset:1024
	ds_read_b128 v[152:155], v213 offset:2048
	ds_read_b128 v[156:159], v213 offset:3072
	s_add_u32 s30, s28, 0x100
	s_addc_u32 s31, s29, 0
	s_cmp_eq_u32 s56, 60
	s_cselect_b32 s37, s3, s31
	s_cselect_b32 s36, s19, s30
	s_cselect_b32 s35, s17, s55
	s_cselect_b32 s34, s25, s54
	v_lshl_add_u64 v[204:205], s[28:29], 0, v[180:181]
	s_add_i32 m0, s27, 0xc000
	ds_read_b128 v[160:163], v214
	ds_read_b128 v[164:167], v214 offset:1024
	ds_read_b128 v[168:171], v214 offset:2048
	ds_read_b128 v[172:175], v214 offset:3072
	ds_read_b128 v[188:191], v214 offset:4096
	ds_read_b128 v[192:195], v214 offset:5120
	ds_read_b128 v[196:199], v214 offset:6144
	ds_read_b128 v[200:203], v214 offset:7168
	global_load_lds_dwordx4 v[204:205], off
	v_lshl_add_u64 v[204:205], s[28:29], 0, v[182:183]
	s_add_i32 m0, s27, 0xe000
	s_nop 0
	global_load_lds_dwordx4 v[204:205], off
	s_waitcnt vmcnt(8)
	s_waitcnt lgkmcnt(0)
	s_setprio 1
	s_barrier
	v_mfma_f32_16x16x32_bf16 v[124:127], v[128:131], v[160:163], v[124:127]
	v_mfma_f32_16x16x32_bf16 v[120:123], v[136:139], v[160:163], v[120:123]
	v_mfma_f32_16x16x32_bf16 v[108:111], v[128:131], v[168:171], v[108:111]
	v_mfma_f32_16x16x32_bf16 v[104:107], v[136:139], v[168:171], v[104:107]
	v_mfma_f32_16x16x32_bf16 v[92:95], v[128:131], v[188:191], v[92:95]
	v_mfma_f32_16x16x32_bf16 v[88:91], v[136:139], v[188:191], v[88:91]
	v_mfma_f32_16x16x32_bf16 v[76:79], v[128:131], v[196:199], v[76:79]
	v_mfma_f32_16x16x32_bf16 v[72:75], v[136:139], v[196:199], v[72:75]
	v_mfma_f32_16x16x32_bf16 v[124:127], v[132:135], v[164:167], v[124:127]
	v_mfma_f32_16x16x32_bf16 v[120:123], v[140:143], v[164:167], v[120:123]
	v_mfma_f32_16x16x32_bf16 v[108:111], v[132:135], v[172:175], v[108:111]
	v_mfma_f32_16x16x32_bf16 v[104:107], v[140:143], v[172:175], v[104:107]
	v_mfma_f32_16x16x32_bf16 v[92:95], v[132:135], v[192:195], v[92:95]
	v_mfma_f32_16x16x32_bf16 v[88:91], v[140:143], v[192:195], v[88:91]
	v_mfma_f32_16x16x32_bf16 v[76:79], v[132:135], v[200:203], v[76:79]
	v_mfma_f32_16x16x32_bf16 v[72:75], v[140:143], v[200:203], v[72:75]
	s_setprio 0
	s_setprio 1
	v_mfma_f32_16x16x32_bf16 v[116:119], v[144:147], v[160:163], v[116:119]
	v_mfma_f32_16x16x32_bf16 v[112:115], v[152:155], v[160:163], v[112:115]
	v_mfma_f32_16x16x32_bf16 v[100:103], v[144:147], v[168:171], v[100:103]
	v_mfma_f32_16x16x32_bf16 v[96:99], v[152:155], v[168:171], v[96:99]
	v_mfma_f32_16x16x32_bf16 v[84:87], v[144:147], v[188:191], v[84:87]
	v_mfma_f32_16x16x32_bf16 v[80:83], v[152:155], v[188:191], v[80:83]
	v_mfma_f32_16x16x32_bf16 v[68:71], v[144:147], v[196:199], v[68:71]
	v_mfma_f32_16x16x32_bf16 v[64:67], v[152:155], v[196:199], v[64:67]
	v_mfma_f32_16x16x32_bf16 v[116:119], v[148:151], v[164:167], v[116:119]
	v_mfma_f32_16x16x32_bf16 v[112:115], v[156:159], v[164:167], v[112:115]
	v_mfma_f32_16x16x32_bf16 v[100:103], v[148:151], v[172:175], v[100:103]
	v_mfma_f32_16x16x32_bf16 v[96:99], v[156:159], v[172:175], v[96:99]
	v_mfma_f32_16x16x32_bf16 v[84:87], v[148:151], v[192:195], v[84:87]
	v_mfma_f32_16x16x32_bf16 v[80:83], v[156:159], v[192:195], v[80:83]
	v_mfma_f32_16x16x32_bf16 v[68:71], v[148:151], v[200:203], v[68:71]
	v_mfma_f32_16x16x32_bf16 v[64:67], v[156:159], v[200:203], v[64:67]
	s_barrier
	s_setprio 0
	s_add_i32 s28, s51, s40
	v_lshl_add_u64 v[204:205], s[34:35], 0, v[176:177]
	s_mov_b32 m0, s28
	ds_read_b128 v[160:163], v214 offset:16384
	ds_read_b128 v[164:167], v214 offset:17408
	ds_read_b128 v[168:171], v214 offset:18432
	ds_read_b128 v[172:175], v214 offset:19456
	ds_read_b128 v[188:191], v214 offset:20480
	ds_read_b128 v[192:195], v214 offset:21504
	ds_read_b128 v[196:199], v214 offset:22528
	ds_read_b128 v[200:203], v214 offset:23552
	global_load_lds_dwordx4 v[204:205], off
	s_add_i32 m0, s28, 0x2000
	s_add_u32 s28, s34, 0x100000
	v_lshl_add_u64 v[216:217], s[34:35], 0, v[178:179]
	s_addc_u32 s29, s35, 0
	s_add_i32 s57, s53, s40
	global_load_lds_dwordx4 v[216:217], off
	v_lshl_add_u64 v[218:219], s[28:29], 0, v[176:177]
	s_mov_b32 m0, s57
	v_lshl_add_u64 v[220:221], s[36:37], 0, v[178:179]
	global_load_lds_dwordx4 v[218:219], off
	v_lshl_add_u64 v[218:219], s[28:29], 0, v[178:179]
	s_add_i32 m0, s57, 0x2000
	s_nop 0
	global_load_lds_dwordx4 v[218:219], off
	v_lshl_add_u64 v[218:219], s[36:37], 0, v[176:177]
	s_mov_b32 m0, s27
	s_nop 0
	global_load_lds_dwordx4 v[218:219], off
	s_mov_b32 m0, s41
	s_nop 0
	global_load_lds_dwordx4 v[220:221], off
	s_waitcnt vmcnt(8)
	s_waitcnt lgkmcnt(0)
	s_setprio 1
	s_barrier
	v_mfma_f32_16x16x32_bf16 v[60:63], v[128:131], v[160:163], v[60:63]
	v_mfma_f32_16x16x32_bf16 v[56:59], v[136:139], v[160:163], v[56:59]
	v_mfma_f32_16x16x32_bf16 v[44:47], v[128:131], v[168:171], v[44:47]
	v_mfma_f32_16x16x32_bf16 v[40:43], v[136:139], v[168:171], v[40:43]
	v_mfma_f32_16x16x32_bf16 v[28:31], v[128:131], v[188:191], v[28:31]
	v_mfma_f32_16x16x32_bf16 v[24:27], v[136:139], v[188:191], v[24:27]
	v_mfma_f32_16x16x32_bf16 v[12:15], v[128:131], v[196:199], v[12:15]
	v_mfma_f32_16x16x32_bf16 v[8:11], v[136:139], v[196:199], v[8:11]
	v_mfma_f32_16x16x32_bf16 v[60:63], v[132:135], v[164:167], v[60:63]
	v_mfma_f32_16x16x32_bf16 v[56:59], v[140:143], v[164:167], v[56:59]
	v_mfma_f32_16x16x32_bf16 v[44:47], v[132:135], v[172:175], v[44:47]
	v_mfma_f32_16x16x32_bf16 v[40:43], v[140:143], v[172:175], v[40:43]
	v_mfma_f32_16x16x32_bf16 v[28:31], v[132:135], v[192:195], v[28:31]
	v_mfma_f32_16x16x32_bf16 v[24:27], v[140:143], v[192:195], v[24:27]
	v_mfma_f32_16x16x32_bf16 v[12:15], v[132:135], v[200:203], v[12:15]
	v_mfma_f32_16x16x32_bf16 v[8:11], v[140:143], v[200:203], v[8:11]
	s_setprio 0
	s_setprio 1
	v_mfma_f32_16x16x32_bf16 v[52:55], v[144:147], v[160:163], v[52:55]
	v_mfma_f32_16x16x32_bf16 v[48:51], v[152:155], v[160:163], v[48:51]
	v_mfma_f32_16x16x32_bf16 v[36:39], v[144:147], v[168:171], v[36:39]
	v_mfma_f32_16x16x32_bf16 v[32:35], v[152:155], v[168:171], v[32:35]
	v_mfma_f32_16x16x32_bf16 v[20:23], v[144:147], v[188:191], v[20:23]
	v_mfma_f32_16x16x32_bf16 v[16:19], v[152:155], v[188:191], v[16:19]
	v_mfma_f32_16x16x32_bf16 v[4:7], v[144:147], v[196:199], v[4:7]
	v_mfma_f32_16x16x32_bf16 v[0:3], v[152:155], v[196:199], v[0:3]
	v_mfma_f32_16x16x32_bf16 v[52:55], v[148:151], v[164:167], v[52:55]
	v_mfma_f32_16x16x32_bf16 v[48:51], v[156:159], v[164:167], v[48:51]
	v_mfma_f32_16x16x32_bf16 v[36:39], v[148:151], v[172:175], v[36:39]
	v_mfma_f32_16x16x32_bf16 v[32:35], v[156:159], v[172:175], v[32:35]
	v_mfma_f32_16x16x32_bf16 v[20:23], v[148:151], v[192:195], v[20:23]
	v_mfma_f32_16x16x32_bf16 v[16:19], v[156:159], v[192:195], v[16:19]
	v_mfma_f32_16x16x32_bf16 v[4:7], v[148:151], v[200:203], v[4:7]
	v_mfma_f32_16x16x32_bf16 v[0:3], v[156:159], v[200:203], v[0:3]
	s_barrier
	s_setprio 0
	s_add_i32 s57, 0, 0x18000
	s_add_i32 s58, 0, 0x1c000
	v_add_u32_e32 v140, s57, v210
	v_add_u32_e32 v156, s58, v210
	ds_read_b128 v[128:131], v140
	ds_read_b128 v[132:135], v140 offset:1024
	ds_read_b128 v[136:139], v140 offset:2048
	ds_read_b128 v[140:143], v140 offset:3072
	ds_read_b128 v[144:147], v156
	ds_read_b128 v[148:151], v156 offset:1024
	ds_read_b128 v[152:155], v156 offset:2048
	ds_read_b128 v[156:159], v156 offset:3072
	s_add_u32 s28, s36, 0x100000
	s_addc_u32 s29, s37, 0
	s_mov_b32 m0, s42
	v_lshl_add_u64 v[222:223], s[28:29], 0, v[176:177]
	ds_read_b128 v[160:163], v214 offset:32768
	ds_read_b128 v[164:167], v214 offset:33792
	ds_read_b128 v[168:171], v214 offset:34816
	ds_read_b128 v[172:175], v214 offset:35840
	ds_read_b128 v[188:191], v214 offset:36864
	ds_read_b128 v[192:195], v214 offset:37888
	ds_read_b128 v[196:199], v214 offset:38912
	ds_read_b128 v[200:203], v214 offset:39936
	global_load_lds_dwordx4 v[222:223], off
	v_lshl_add_u64 v[222:223], s[28:29], 0, v[178:179]
	s_mov_b32 m0, s43
	s_nop 0
	global_load_lds_dwordx4 v[222:223], off
	s_waitcnt vmcnt(8)
	s_waitcnt lgkmcnt(0)
	s_setprio 1
	s_barrier
	v_mfma_f32_16x16x32_bf16 v[124:127], v[128:131], v[160:163], v[124:127]
	v_mfma_f32_16x16x32_bf16 v[120:123], v[136:139], v[160:163], v[120:123]
	v_mfma_f32_16x16x32_bf16 v[108:111], v[128:131], v[168:171], v[108:111]
	v_mfma_f32_16x16x32_bf16 v[104:107], v[136:139], v[168:171], v[104:107]
	v_mfma_f32_16x16x32_bf16 v[92:95], v[128:131], v[188:191], v[92:95]
	v_mfma_f32_16x16x32_bf16 v[88:91], v[136:139], v[188:191], v[88:91]
	v_mfma_f32_16x16x32_bf16 v[76:79], v[128:131], v[196:199], v[76:79]
	v_mfma_f32_16x16x32_bf16 v[72:75], v[136:139], v[196:199], v[72:75]
	v_mfma_f32_16x16x32_bf16 v[124:127], v[132:135], v[164:167], v[124:127]
	v_mfma_f32_16x16x32_bf16 v[120:123], v[140:143], v[164:167], v[120:123]
	v_mfma_f32_16x16x32_bf16 v[108:111], v[132:135], v[172:175], v[108:111]
	v_mfma_f32_16x16x32_bf16 v[104:107], v[140:143], v[172:175], v[104:107]
	v_mfma_f32_16x16x32_bf16 v[92:95], v[132:135], v[192:195], v[92:95]
	v_mfma_f32_16x16x32_bf16 v[88:91], v[140:143], v[192:195], v[88:91]
	v_mfma_f32_16x16x32_bf16 v[76:79], v[132:135], v[200:203], v[76:79]
	v_mfma_f32_16x16x32_bf16 v[72:75], v[140:143], v[200:203], v[72:75]
	s_setprio 0
	s_setprio 1
	v_mfma_f32_16x16x32_bf16 v[116:119], v[144:147], v[160:163], v[116:119]
	v_mfma_f32_16x16x32_bf16 v[112:115], v[152:155], v[160:163], v[112:115]
	v_mfma_f32_16x16x32_bf16 v[100:103], v[144:147], v[168:171], v[100:103]
	v_mfma_f32_16x16x32_bf16 v[96:99], v[152:155], v[168:171], v[96:99]
	v_mfma_f32_16x16x32_bf16 v[84:87], v[144:147], v[188:191], v[84:87]
	v_mfma_f32_16x16x32_bf16 v[80:83], v[152:155], v[188:191], v[80:83]
	v_mfma_f32_16x16x32_bf16 v[68:71], v[144:147], v[196:199], v[68:71]
	v_mfma_f32_16x16x32_bf16 v[64:67], v[152:155], v[196:199], v[64:67]
	v_mfma_f32_16x16x32_bf16 v[116:119], v[148:151], v[164:167], v[116:119]
	v_mfma_f32_16x16x32_bf16 v[112:115], v[156:159], v[164:167], v[112:115]
	v_mfma_f32_16x16x32_bf16 v[100:103], v[148:151], v[172:175], v[100:103]
	v_mfma_f32_16x16x32_bf16 v[96:99], v[156:159], v[172:175], v[96:99]
	v_mfma_f32_16x16x32_bf16 v[84:87], v[148:151], v[192:195], v[84:87]
	v_mfma_f32_16x16x32_bf16 v[80:83], v[156:159], v[192:195], v[80:83]
	v_mfma_f32_16x16x32_bf16 v[68:71], v[148:151], v[200:203], v[68:71]
	v_mfma_f32_16x16x32_bf16 v[64:67], v[156:159], v[200:203], v[64:67]
	s_barrier
	s_setprio 0
	s_add_i32 s28, s57, s40
	v_lshl_add_u64 v[204:205], v[204:205], 0, s[12:13]
	s_mov_b32 m0, s28
	ds_read_b128 v[160:163], v214 offset:49152
	ds_read_b128 v[164:167], v214 offset:50176
	ds_read_b128 v[168:171], v214 offset:51200
	ds_read_b128 v[172:175], v214 offset:52224
	ds_read_b128 v[188:191], v214 offset:53248
	ds_read_b128 v[192:195], v214 offset:54272
	ds_read_b128 v[196:199], v214 offset:55296
	ds_read_b128 v[200:203], v214 offset:56320
	global_load_lds_dwordx4 v[204:205], off
	s_add_i32 m0, s28, 0x2000
	s_add_u32 s28, s34, 0x100080
	v_lshl_add_u64 v[204:205], v[216:217], 0, s[12:13]
	s_addc_u32 s29, s35, 0
	s_add_i32 s34, s58, s40
	global_load_lds_dwordx4 v[204:205], off
	v_lshl_add_u64 v[204:205], s[28:29], 0, v[176:177]
	s_mov_b32 m0, s34
	s_nop 0
	global_load_lds_dwordx4 v[204:205], off
	v_lshl_add_u64 v[204:205], s[28:29], 0, v[178:179]
	s_add_i32 m0, s34, 0x2000
	s_nop 0
	global_load_lds_dwordx4 v[204:205], off
	v_lshl_add_u64 v[204:205], v[218:219], 0, s[12:13]
	s_mov_b32 m0, s45
	s_nop 0
	global_load_lds_dwordx4 v[204:205], off
	v_lshl_add_u64 v[204:205], v[220:221], 0, s[12:13]
	s_mov_b32 m0, s48
	s_nop 0
	global_load_lds_dwordx4 v[204:205], off
	s_waitcnt vmcnt(8)
	s_waitcnt lgkmcnt(0)
	s_setprio 1
	s_barrier
	v_mfma_f32_16x16x32_bf16 v[60:63], v[128:131], v[160:163], v[60:63]
	v_mfma_f32_16x16x32_bf16 v[56:59], v[136:139], v[160:163], v[56:59]
	v_mfma_f32_16x16x32_bf16 v[44:47], v[128:131], v[168:171], v[44:47]
	v_mfma_f32_16x16x32_bf16 v[40:43], v[136:139], v[168:171], v[40:43]
	v_mfma_f32_16x16x32_bf16 v[28:31], v[128:131], v[188:191], v[28:31]
	v_mfma_f32_16x16x32_bf16 v[24:27], v[136:139], v[188:191], v[24:27]
	v_mfma_f32_16x16x32_bf16 v[12:15], v[128:131], v[196:199], v[12:15]
	v_mfma_f32_16x16x32_bf16 v[8:11], v[136:139], v[196:199], v[8:11]
	v_mfma_f32_16x16x32_bf16 v[60:63], v[132:135], v[164:167], v[60:63]
	v_mfma_f32_16x16x32_bf16 v[56:59], v[140:143], v[164:167], v[56:59]
	v_mfma_f32_16x16x32_bf16 v[44:47], v[132:135], v[172:175], v[44:47]
	v_mfma_f32_16x16x32_bf16 v[40:43], v[140:143], v[172:175], v[40:43]
	v_mfma_f32_16x16x32_bf16 v[28:31], v[132:135], v[192:195], v[28:31]
	v_mfma_f32_16x16x32_bf16 v[24:27], v[140:143], v[192:195], v[24:27]
	v_mfma_f32_16x16x32_bf16 v[12:15], v[132:135], v[200:203], v[12:15]
	v_mfma_f32_16x16x32_bf16 v[8:11], v[140:143], v[200:203], v[8:11]
	s_setprio 0
	s_setprio 1
	v_mfma_f32_16x16x32_bf16 v[52:55], v[144:147], v[160:163], v[52:55]
	v_mfma_f32_16x16x32_bf16 v[48:51], v[152:155], v[160:163], v[48:51]
	v_mfma_f32_16x16x32_bf16 v[36:39], v[144:147], v[168:171], v[36:39]
	v_mfma_f32_16x16x32_bf16 v[32:35], v[152:155], v[168:171], v[32:35]
	v_mfma_f32_16x16x32_bf16 v[20:23], v[144:147], v[188:191], v[20:23]
	v_mfma_f32_16x16x32_bf16 v[16:19], v[152:155], v[188:191], v[16:19]
	v_mfma_f32_16x16x32_bf16 v[4:7], v[144:147], v[196:199], v[4:7]
	v_mfma_f32_16x16x32_bf16 v[0:3], v[152:155], v[196:199], v[0:3]
	v_mfma_f32_16x16x32_bf16 v[52:55], v[148:151], v[164:167], v[52:55]
	v_mfma_f32_16x16x32_bf16 v[48:51], v[156:159], v[164:167], v[48:51]
	v_mfma_f32_16x16x32_bf16 v[36:39], v[148:151], v[172:175], v[36:39]
	v_mfma_f32_16x16x32_bf16 v[32:35], v[156:159], v[172:175], v[32:35]
	v_mfma_f32_16x16x32_bf16 v[20:23], v[148:151], v[192:195], v[20:23]
	v_mfma_f32_16x16x32_bf16 v[16:19], v[156:159], v[192:195], v[16:19]
	v_mfma_f32_16x16x32_bf16 v[4:7], v[148:151], v[200:203], v[4:7]
	v_mfma_f32_16x16x32_bf16 v[0:3], v[156:159], v[200:203], v[0:3]
	s_barrier
	s_setprio 0
	s_add_i32 s56, s56, 2
	s_add_u32 s54, s54, 0x100
	s_addc_u32 s55, s55, 0
	s_cmp_gt_u32 s56, 61
	s_mov_b64 s[28:29], s[30:31]
	s_cbranch_scc0 .LBB0_1389
	s_nop 0
	s_nop 0
	s_nop 0
	s_and_b64 vcc, exec, s[14:15]
	s_cbranch_vccz .LBB0_1392
	s_barrier
